# XCD-local barriers: the leader releases its XCD before issuing its own L1 invalidate
# baseline (speedup 1.0000x reference)
; __device__ __forceinline__ unsigned xb_ld(unsigned* p)              { return __hip_atomic_load(p, __ATOMIC_RELAXED, __HIP_MEMORY_SCOPE_AGENT); }
; __device__ __forceinline__ unsigned xb_add(unsigned* p, unsigned v) { return __hip_atomic_fetch_add(p, v, __ATOMIC_RELAXED, __HIP_MEMORY_SCOPE_AGENT); }
; #define XB_SPIN(cond, bar) do { unsigned _sp = 0; while (cond) { __builtin_amdgcn_s_sleep(1); \
;     if ((++_sp & 255u) == 0u) { if (xb_ld(&(bar)[XB_TMO])) break; if (_sp > XB_SPIN_CAP) { atomicAdd(&(bar)[XB_TMO], 1u); break; } } } } while (0)
; __device__ __forceinline__ void xcd_barrier(const XcdBarrier& b) {
;     ...
;         const unsigned old = xb_add(&bar[XB_XSUB(b.x)], 1u);
;         const unsigned gen = old / nloc;
;         if (old + 1u == (gen + 1u) * nloc) {
;             __builtin_amdgcn_fence(__ATOMIC_RELEASE, "agent");
;             asm volatile("s_waitcnt vmcnt(0)" ::: "memory");
;             const unsigned og = xb_add(&bar[XB_TOP], 1u);
;             const unsigned tg = og / nx;
;             if (og + 1u == (tg + 1u) * nx) xb_add(&bar[XB_TOPGEN], 1u);
;             else XB_SPIN(xb_ld(&bar[XB_TOPGEN]) == tg, bar);
;             __builtin_amdgcn_fence(__ATOMIC_ACQUIRE, "agent");
;             xb_add(&bar[XB_XGEN(b.x)], 1u);
;             asm volatile("s_waitcnt vmcnt(0)" ::: "memory");
;         } else {
;             XB_SPIN(xb_ld(&bar[XB_XGEN(b.x)]) == gen, bar);
;             __builtin_amdgcn_fence(__ATOMIC_ACQUIRE, "agent");
.LBB0_451:
	s_andn2_saveexec_b64 s[4:5], s[4:5]
	s_cbranch_execz .LBB0_471
	s_mov_b64 s[4:5], exec
	v_readfirstlane_b32 s98, v238
	s_cmp_eq_u32 s98, 0
	s_cbranch_scc0 .Lfullbar_3ab
	s_branch .LBB0_468

; __device__ __forceinline__ unsigned xb_add(unsigned* p, unsigned v) { return __hip_atomic_fetch_add(p, v, __ATOMIC_RELAXED, __HIP_MEMORY_SCOPE_AGENT); }
; __device__ __forceinline__ void xcd_barrier(const XcdBarrier& b) {
;     ...
;             xb_add(&bar[XB_XGEN(b.x)], 1u);
;             asm volatile("s_waitcnt vmcnt(0)" ::: "memory");
.LBB0_468:
	s_or_b64 exec, exec, s[4:5]
	s_mov_b64 s[4:5], exec
	v_mbcnt_lo_u32_b32 v0, s4, 0
	v_mbcnt_hi_u32_b32 v0, s5, v0
	v_cmp_eq_u32_e32 vcc, 0, v0
	s_waitcnt vmcnt(0)
	s_and_saveexec_b64 s[6:7], vcc
	s_cbranch_execz .LBB0_470
	s_bcnt1_i32_b64 s4, s[4:5]
	v_mov_b32_e32 v0, 0x2000
	v_mov_b32_e32 v1, s4
	global_atomic_add v0, v1, s[2:3] offset:1024
	buffer_inv sc1

; __device__ __forceinline__ unsigned xb_ld(unsigned* p)              { return __hip_atomic_load(p, __ATOMIC_RELAXED, __HIP_MEMORY_SCOPE_AGENT); }
; __device__ __forceinline__ unsigned xb_add(unsigned* p, unsigned v) { return __hip_atomic_fetch_add(p, v, __ATOMIC_RELAXED, __HIP_MEMORY_SCOPE_AGENT); }
; #define XB_SPIN(cond, bar) do { unsigned _sp = 0; while (cond) { __builtin_amdgcn_s_sleep(1); \
;     if ((++_sp & 255u) == 0u) { if (xb_ld(&(bar)[XB_TMO])) break; if (_sp > XB_SPIN_CAP) { atomicAdd(&(bar)[XB_TMO], 1u); break; } } } } while (0)
; __device__ __forceinline__ void xcd_barrier(const XcdBarrier& b) {
;     ...
;         const unsigned old = xb_add(&bar[XB_XSUB(b.x)], 1u);
;         const unsigned gen = old / nloc;
;         if (old + 1u == (gen + 1u) * nloc) {
;             __builtin_amdgcn_fence(__ATOMIC_RELEASE, "agent");
;             asm volatile("s_waitcnt vmcnt(0)" ::: "memory");
;             const unsigned og = xb_add(&bar[XB_TOP], 1u);
;             const unsigned tg = og / nx;
;             if (og + 1u == (tg + 1u) * nx) xb_add(&bar[XB_TOPGEN], 1u);
;             else XB_SPIN(xb_ld(&bar[XB_TOPGEN]) == tg, bar);
;             __builtin_amdgcn_fence(__ATOMIC_ACQUIRE, "agent");
;             xb_add(&bar[XB_XGEN(b.x)], 1u);
;             asm volatile("s_waitcnt vmcnt(0)" ::: "memory");
;         } else {
;             XB_SPIN(xb_ld(&bar[XB_XGEN(b.x)]) == gen, bar);
;             __builtin_amdgcn_fence(__ATOMIC_ACQUIRE, "agent");
.LBB0_949:
	s_andn2_saveexec_b64 s[6:7], s[6:7]
	s_cbranch_execz .LBB0_969
	s_mov_b64 s[6:7], exec
	v_readfirstlane_b32 s98, v238
	s_cmp_eq_u32 s98, 0
	s_cbranch_scc0 .Lfullbar_57
	s_branch .LBB0_966

; __device__ __forceinline__ unsigned xb_add(unsigned* p, unsigned v) { return __hip_atomic_fetch_add(p, v, __ATOMIC_RELAXED, __HIP_MEMORY_SCOPE_AGENT); }
; __device__ __forceinline__ void xcd_barrier(const XcdBarrier& b) {
;     ...
;             xb_add(&bar[XB_XGEN(b.x)], 1u);
;             asm volatile("s_waitcnt vmcnt(0)" ::: "memory");
.LBB0_966:
	s_or_b64 exec, exec, s[6:7]
	s_mov_b64 s[6:7], exec
	v_mbcnt_lo_u32_b32 v0, s6, 0
	v_mbcnt_hi_u32_b32 v0, s7, v0
	v_cmp_eq_u32_e32 vcc, 0, v0
	s_waitcnt vmcnt(0)
	s_and_saveexec_b64 s[10:11], vcc
	s_cbranch_execz .LBB0_968
	s_bcnt1_i32_b64 s6, s[6:7]
	v_mov_b32_e32 v0, 0x2000
	v_mov_b32_e32 v1, s6
	global_atomic_add v0, v1, s[4:5] offset:1024
	buffer_inv sc1

; __device__ __forceinline__ unsigned xb_add(unsigned* p, unsigned v) { return __hip_atomic_fetch_add(p, v, __ATOMIC_RELAXED, __HIP_MEMORY_SCOPE_AGENT); }
; __device__ __forceinline__ void xcd_barrier(const XcdBarrier& b) {
;     ...
;             xb_add(&bar[XB_XGEN(b.x)], 1u);
;             asm volatile("s_waitcnt vmcnt(0)" ::: "memory");
.LBB0_1050:
	s_or_b64 exec, exec, s[6:7]
	s_mov_b64 s[6:7], exec
	v_mbcnt_lo_u32_b32 v0, s6, 0
	v_mbcnt_hi_u32_b32 v0, s7, v0
	v_cmp_eq_u32_e32 vcc, 0, v0
	s_waitcnt vmcnt(0)
	s_and_saveexec_b64 s[8:9], vcc
	s_cbranch_execz .LBB0_1052
	s_bcnt1_i32_b64 s6, s[6:7]
	v_mov_b32_e32 v0, 0x2000
	v_mov_b32_e32 v1, s6
	global_atomic_add v0, v1, s[4:5] offset:1024
	buffer_inv sc1
